# filter nb-loop: 4-byte VOP1/VOP2 ops re-encoded as VOP3 where that puts the following 8-byte instructions (loads, VOP3, MFMA) on 8-byte boundaries
# baseline (speedup 1.0000x reference)
; DI void filter_tile(const P& p, int l, int tile, char* smem) {
;     ...
;   for (int nb = 0; nb < 8; nb += 2) {
;     u32x4 bw[2][4];
; #pragma unroll
;     for (int u = 0; u < 2; ++u) {
;       const int col = wave * 256 + (nb + u) * 32 + li;
; #pragma unroll
;       for (int ks = 0; ks < 4; ++ks) {
;         const float* wp = w4 + (size_t)(16 * ks + 8 * g) * 2048 + col;
;         const float a0 = wp[0], a1 = wp[2048], a2 = wp[2 * 2048], a3 = wp[3 * 2048];
;         const float a4 = wp[4 * 2048], a5 = wp[5 * 2048], a6 = wp[6 * 2048], a7 = wp[7 * 2048];
;         u32x4 t; t[0] = pack2(a0, a1); t[1] = pack2(a2, a3); t[2] = pack2(a4, a5); t[3] = pack2(a6, a7);
;         bw[u][ks] = t;
;       }
;     }
.LBB0_183:
	v_lshrrev_b32_e64 v241, 6, v198
	v_mul_u32_u24_e32 v241, 0x900, v241
	v_add_u32_e32 v241, 0x10000, v241
	v_and_b32_e64 v242, 31, v198
	v_bfe_u32 v243, v198, 5, 1
	v_mul_u32_u24_e32 v222, 0x44, v242
	v_lshl_add_u32 v222, v243, 3, v222
	v_add_u32_e64 v222, v222, v241
	v_mul_u32_u24_e32 v223, 0x44, v243
	v_lshl_add_u32 v223, v242, 1, v223
	v_add_u32_e32 v223, v223, v241
	v_add_u32_e32 v244, s64, v242
	v_sub_u32_e32 v245, 0x2000, v244
	v_add_u32_e32 v244, 0x2000, v244
	v_cndmask_b32_e64 v244, v245, v244, s[6:7]
	v_lshlrev_b32_e64 v244, 1, v244
	v_lshl_add_u32 v240, v243, 15, v244
	v_ashrrev_i32_e64 v77, 31, v76
	v_lshl_add_u64 v[4:5], v[76:77], 2, s[70:71]
	v_lshl_add_u64 v[84:85], v[40:41], 2, v[4:5]
	v_add_co_u32_e32 v86, vcc, 0x2000, v84
	s_waitcnt lgkmcnt(0)
	v_lshl_add_u64 v[0:1], v[4:5], 0, v[78:79]
	v_addc_co_u32_e32 v87, vcc, 0, v85, vcc
	v_add_co_u32_e32 v88, vcc, 0x4000, v84
	global_load_dword v90, v[0:1], off
	s_nop 0
	v_addc_co_u32_e32 v89, vcc, 0, v85, vcc
	v_add_co_u32_e32 v6, vcc, 0x6000, v84
	global_load_dword v32, v[84:85], off
	s_nop 0
	v_addc_co_u32_e32 v7, vcc, 0, v85, vcc
	v_add_co_u32_e32 v8, vcc, 0x8000, v84
	global_load_dword v35, v[6:7], off
	s_nop 0
	v_addc_co_u32_e32 v9, vcc, 0, v85, vcc
	v_add_co_u32_e32 v12, vcc, 0xa000, v84
	global_load_dword v36, v[8:9], off
	s_nop 0
	v_addc_co_u32_e32 v13, vcc, 0, v85, vcc
	v_add_co_u32_e32 v14, vcc, 0xc000, v84
	global_load_dword v37, v[12:13], off
	s_nop 0
	v_addc_co_u32_e32 v15, vcc, 0, v85, vcc
	v_add_co_u32_e32 v10, vcc, 0xe000, v84
	global_load_dword v38, v[14:15], off
	s_nop 0
	v_addc_co_u32_e32 v11, vcc, 0, v85, vcc
	v_add_co_u32_e32 v2, vcc, s65, v0
	global_load_dword v39, v[10:11], off
	s_nop 0
	v_addc_co_u32_e32 v3, vcc, 0, v1, vcc
	global_load_dword v91, v[2:3], off
	v_add_co_u32_e32 v2, vcc, s61, v0
	global_load_dword v33, v[86:87], off
	s_nop 0
	v_addc_co_u32_e32 v3, vcc, 0, v1, vcc
	global_load_dword v92, v[2:3], off
	v_add_co_u32_e32 v2, vcc, s2, v0
	global_load_dword v34, v[88:89], off
	s_nop 0
	v_addc_co_u32_e32 v3, vcc, 0, v1, vcc
	global_load_dword v93, v[2:3], off
	v_add_co_u32_e32 v2, vcc, s1, v0
	s_nop 1
	v_addc_co_u32_e32 v3, vcc, 0, v1, vcc
	global_load_dword v94, v[2:3], off
	v_add_co_u32_e32 v2, vcc, s62, v0
	s_nop 1
	v_addc_co_u32_e32 v3, vcc, 0, v1, vcc
	global_load_dword v95, v[2:3], off
	v_add_co_u32_e32 v2, vcc, s63, v0
	s_nop 1
	v_addc_co_u32_e32 v3, vcc, 0, v1, vcc
	v_add_co_u32_e32 v0, vcc, s33, v0
	global_load_dword v96, v[2:3], off
	s_nop 0
	v_addc_co_u32_e32 v1, vcc, 0, v1, vcc
	global_load_dword v97, v[0:1], off
	v_lshl_add_u64 v[0:1], v[4:5], 0, v[80:81]
	v_add_co_u32_e32 v2, vcc, s65, v0
	global_load_dword v98, v[0:1], off
	s_nop 0
	v_addc_co_u32_e32 v3, vcc, 0, v1, vcc
	global_load_dword v99, v[2:3], off
	v_add_co_u32_e32 v2, vcc, s61, v0
	s_nop 1
	v_addc_co_u32_e32 v3, vcc, 0, v1, vcc
	global_load_dword v100, v[2:3], off
	v_add_co_u32_e32 v2, vcc, s2, v0
	s_nop 1
	v_addc_co_u32_e32 v3, vcc, 0, v1, vcc
	global_load_dword v101, v[2:3], off
	v_add_co_u32_e32 v2, vcc, s1, v0
	s_nop 1
	v_addc_co_u32_e32 v3, vcc, 0, v1, vcc
	global_load_dword v102, v[2:3], off
	v_add_co_u32_e32 v2, vcc, s62, v0
	s_nop 1
	v_addc_co_u32_e32 v3, vcc, 0, v1, vcc
	global_load_dword v103, v[2:3], off
	v_add_co_u32_e32 v2, vcc, s63, v0
	s_nop 1
	v_addc_co_u32_e32 v3, vcc, 0, v1, vcc
	v_add_co_u32_e32 v0, vcc, s33, v0
	global_load_dword v104, v[2:3], off
	s_nop 0
	v_addc_co_u32_e32 v1, vcc, 0, v1, vcc
	global_load_dword v105, v[0:1], off
	s_waitcnt vmcnt(19)
	v_cvt_pk_bf16_f32 v2, v36, v37
	s_waitcnt vmcnt(17)
	v_cvt_pk_bf16_f32 v3, v38, v39
	s_waitcnt vmcnt(16)
	v_cvt_pk_bf16_f32 v36, v90, v91
	s_waitcnt vmcnt(15)
	v_cvt_pk_bf16_f32 v0, v32, v33
	s_waitcnt vmcnt(13)
	v_cvt_pk_bf16_f32 v1, v34, v35
	s_waitcnt vmcnt(12)
	v_cvt_pk_bf16_f32 v37, v92, v93
	s_waitcnt vmcnt(10)
	v_cvt_pk_bf16_f32 v38, v94, v95
	s_waitcnt vmcnt(8)
	v_cvt_pk_bf16_f32 v39, v96, v97
	s_waitcnt vmcnt(6)
	v_cvt_pk_bf16_f32 v32, v98, v99
	v_lshl_add_u64 v[98:99], v[4:5], 0, v[82:83]
	v_add_co_u32_e32 v90, vcc, s65, v98
	global_load_dword v92, v[98:99], off
	s_nop 0
	v_addc_co_u32_e32 v91, vcc, 0, v99, vcc
	global_load_dword v94, v[90:91], off
	v_add_co_u32_e32 v90, vcc, s61, v98
	v_lshl_add_u64 v[4:5], v[4:5], 0, s[58:59]
	s_nop 0
	v_addc_co_u32_e32 v91, vcc, 0, v99, vcc
	global_load_dword v96, v[90:91], off
	v_add_co_u32_e32 v90, vcc, s2, v98
	s_waitcnt vmcnt(7)
	v_cvt_pk_bf16_f32 v33, v100, v101
	v_addc_co_u32_e32 v91, vcc, 0, v99, vcc
	global_load_dword v97, v[90:91], off
	v_add_co_u32_e32 v90, vcc, s1, v98
	s_waitcnt vmcnt(6)
	v_cvt_pk_bf16_f32 v34, v102, v103
	v_addc_co_u32_e32 v91, vcc, 0, v99, vcc
	v_add_co_u32_e32 v100, vcc, s62, v98
	global_load_dword v90, v[90:91], off
	s_nop 0
	v_addc_co_u32_e32 v101, vcc, 0, v99, vcc
	global_load_dword v91, v[100:101], off
	v_add_co_u32_e32 v100, vcc, s63, v98
	s_waitcnt vmcnt(6)
; #define MFMA(a, b, c) __builtin_amdgcn_mfma_f32_32x32x16_bf16((a), (b), (c), 0, 0, 0)
; DI f32x16 zero16() { f32x16 z; for (int i = 0; i < 16; ++i) z[i] = 0.f; return z; }
; DI void filter_tile(const P& p, int l, int tile, char* smem) {
;     ...
; #pragma unroll
;     for (int u = 0; u < 2; ++u) {
;       const int col = wave * 256 + (nb + u) * 32 + li;
; #pragma unroll
;       for (int ks = 0; ks < 4; ++ks) {
;         const float* wp = w4 + (size_t)(16 * ks + 8 * g) * 2048 + col;
;         const float a0 = wp[0], a1 = wp[2048], a2 = wp[2 * 2048], a3 = wp[3 * 2048];
;         const float a4 = wp[4 * 2048], a5 = wp[5 * 2048], a6 = wp[6 * 2048], a7 = wp[7 * 2048];
;         u32x4 t; t[0] = pack2(a0, a1); t[1] = pack2(a2, a3); t[2] = pack2(a4, a5); t[3] = pack2(a6, a7);
;         bw[u][ks] = t;
;       }
;     }
; #pragma unroll
;     for (int u = 0; u < 2; ++u) {
;       const int col = wave * 256 + (nb + u) * 32 + li;
;       f32x16 acc = zero16();
; #pragma unroll
;       for (int ks = 0; ks < 4; ++ks) acc = MFMA(af[ks], __builtin_bit_cast(bf16x8, bw[u][ks]), acc);
;       const int j = col >> 9, c = col & 511;
;       const int order = j & 1;
;       const bool fwd = j < 2;
;       const float delta = fabsf(min_decay + (float)c * ((max_decay - min_decay) / 511.0f));
	v_cvt_pk_bf16_f32 v35, v104, v105
	v_addc_co_u32_e32 v101, vcc, 0, v99, vcc
	v_add_co_u32_e32 v98, vcc, s33, v98
	global_load_dword v93, v[100:101], off
	s_nop 0
	v_addc_co_u32_e32 v99, vcc, 0, v99, vcc
	global_load_dword v95, v[98:99], off
	global_load_dword v112, v[84:85], off offset:128
	global_load_dword v113, v[86:87], off offset:128
	global_load_dword v115, v[88:89], off offset:128
	global_load_dword v116, v[6:7], off offset:128
	global_load_dword v117, v[8:9], off offset:128
	global_load_dword v118, v[12:13], off offset:128
	global_load_dword v119, v[14:15], off offset:128
	global_load_dword v120, v[10:11], off offset:128
	v_lshl_add_u64 v[6:7], v[4:5], 0, v[78:79]
	v_add_co_u32_e32 v8, vcc, s65, v6
	global_load_dword v121, v[6:7], off
	s_nop 0
	v_addc_co_u32_e32 v9, vcc, 0, v7, vcc
	global_load_dword v122, v[8:9], off
	v_add_co_u32_e32 v8, vcc, s61, v6
	v_lshl_add_u64 v[84:85], v[4:5], 0, v[82:83]
	s_nop 0
	v_addc_co_u32_e32 v9, vcc, 0, v7, vcc
	global_load_dword v123, v[8:9], off
	v_add_co_u32_e32 v8, vcc, s2, v6
	global_load_dword v137, v[84:85], off
	s_nop 0
	v_addc_co_u32_e32 v9, vcc, 0, v7, vcc
	global_load_dword v124, v[8:9], off
	v_add_co_u32_e32 v8, vcc, s1, v6
	s_nop 1
	v_addc_co_u32_e32 v9, vcc, 0, v7, vcc
	global_load_dword v125, v[8:9], off
	v_add_co_u32_e32 v8, vcc, s62, v6
	s_nop 1
	v_addc_co_u32_e32 v9, vcc, 0, v7, vcc
	global_load_dword v126, v[8:9], off
	v_add_co_u32_e32 v8, vcc, s63, v6
	s_nop 1
	v_addc_co_u32_e32 v9, vcc, 0, v7, vcc
	v_add_co_u32_e32 v6, vcc, s33, v6
	global_load_dword v127, v[8:9], off
	s_nop 0
	v_addc_co_u32_e32 v7, vcc, 0, v7, vcc
	global_load_dword v128, v[6:7], off
	v_lshl_add_u64 v[6:7], v[4:5], 0, v[80:81]
	v_add_co_u32_e32 v8, vcc, s65, v6
	global_load_dword v129, v[6:7], off
	s_nop 0
	v_addc_co_u32_e32 v9, vcc, 0, v7, vcc
	global_load_dword v130, v[8:9], off
	v_add_co_u32_e32 v8, vcc, s61, v6
	s_nop 1
	v_addc_co_u32_e32 v9, vcc, 0, v7, vcc
	global_load_dword v131, v[8:9], off
	v_add_co_u32_e32 v8, vcc, s2, v6
	s_nop 1
	v_addc_co_u32_e32 v9, vcc, 0, v7, vcc
	global_load_dword v132, v[8:9], off
	v_add_co_u32_e32 v8, vcc, s1, v6
	s_nop 1
	v_addc_co_u32_e32 v9, vcc, 0, v7, vcc
	global_load_dword v133, v[8:9], off
	v_add_co_u32_e32 v8, vcc, s62, v6
	s_nop 1
	v_addc_co_u32_e32 v9, vcc, 0, v7, vcc
	global_load_dword v134, v[8:9], off
	v_add_co_u32_e32 v8, vcc, s63, v6
	s_nop 1
	v_addc_co_u32_e32 v9, vcc, 0, v7, vcc
	v_add_co_u32_e32 v6, vcc, s33, v6
	global_load_dword v135, v[8:9], off
	s_nop 0
	v_addc_co_u32_e32 v7, vcc, 0, v7, vcc
	v_add_co_u32_e32 v4, vcc, s65, v84
	global_load_dword v136, v[6:7], off
	s_nop 0
	v_addc_co_u32_e32 v5, vcc, 0, v85, vcc
	global_load_dword v138, v[4:5], off
	v_add_co_u32_e32 v4, vcc, s61, v84
	s_nop 1
	v_addc_co_u32_e32 v5, vcc, 0, v85, vcc
	global_load_dword v139, v[4:5], off
	v_add_co_u32_e32 v4, vcc, s2, v84
	s_nop 1
	v_addc_co_u32_e32 v5, vcc, 0, v85, vcc
	global_load_dword v141, v[4:5], off
	v_add_co_u32_e32 v4, vcc, s1, v84
	s_nop 1
	v_addc_co_u32_e32 v5, vcc, 0, v85, vcc
	v_add_co_u32_e32 v86, vcc, s62, v84
	global_load_dword v140, v[4:5], off
	s_nop 0
	v_addc_co_u32_e32 v87, vcc, 0, v85, vcc
	global_load_dword v142, v[86:87], off
	s_waitcnt lgkmcnt(3)
	v_mfma_f32_32x32x16_bf16 v[0:15], v[16:19], v[0:3], 0
	v_add_co_u32_e32 v86, vcc, s63, v84
	s_nop 1
	v_addc_co_u32_e32 v87, vcc, 0, v85, vcc
	global_load_dword v143, v[86:87], off
	s_waitcnt lgkmcnt(2)
	v_mfma_f32_32x32x16_bf16 v[0:15], v[20:23], v[36:39], v[0:15]
	v_add_co_u32_e32 v36, vcc, s33, v84
	s_nop 1
	v_addc_co_u32_e32 v37, vcc, 0, v85, vcc
	global_load_dword v144, v[36:37], off
	v_and_b32_e32 v37, 0x1df, v76
	s_waitcnt lgkmcnt(1)
	v_mfma_f32_32x32x16_bf16 v[0:15], v[24:27], v[32:35], v[0:15]
	v_cvt_f32_u32_e32 v36, v37
	s_waitcnt vmcnt(38)
	v_cvt_pk_bf16_f32 v32, v92, v94
	s_waitcnt vmcnt(36)
	v_cvt_pk_bf16_f32 v33, v96, v97
	s_waitcnt vmcnt(34)
	v_cvt_pk_bf16_f32 v34, v90, v91
	s_waitcnt vmcnt(32)
	v_cvt_pk_bf16_f32 v35, v93, v95
	v_fmamk_f32 v36, v36, 0xbcc4df2d, v201
	s_waitcnt lgkmcnt(0)
; DI u16 f2bf(float a) { return (u16)(pack2(a, 0.f) & 0xffffu); }
; DI int crow(int reg, int g) { return (reg & 3) + 8 * (reg >> 2) + 4 * g; }
; DI void filter_tile(const P& p, int l, int tile, char* smem) {
;     ...
;       const int j = col >> 9, c = col & 511;
;       const int order = j & 1;
;       const bool fwd = j < 2;
;       const float delta = fabsf(min_decay + (float)c * ((max_decay - min_decay) / 511.0f));
;       u16* tb = p.Tb + (size_t)(order * 512 + c) * 16384;
;       float asum = 0.f;
; #pragma unroll
;       for (int reg = 0; reg < 16; ++reg) {
;         const int m = m0 + crow(reg, g);
;         const float t = (float)m / 8191.0f;
;         const float v = acc[reg] * __expf(-t * delta);
;         if (fwd) { tb[8192 - m] = f2bf(v); asum += fabsf(v); }
;         else if (m >= 1) { tb[8192 + m] = f2bf(v); asum += fabsf(v); }
;       }
	v_mfma_f32_32x32x16_bf16 v[0:15], v[28:31], v[32:35], v[0:15]
	v_mul_f32_e64 v32, v47, |v36|
	v_mul_f32_e32 v32, 0x3fb8aa3b, v32
	v_exp_f32_e32 v32, v32
	v_or_b32_e32 v33, v37, v43
	v_lshlrev_b32_e64 v188, 15, v33
	v_lshl_add_u64 v[34:35], s[44:45], 0, v[188:189]
	s_nop 5
	v_mul_f32_e32 v32, v32, v0
	v_and_b32_e32 v0, 0x7fffffff, v32
	v_cvt_pk_bf16_f32 v241, v32, s0
	ds_write_b16 v222, v241 offset:0
	s_andn2_b64 s[80:81], s[6:7], s[10:11]
	v_cndmask_b32_e64 v0, v0, 0, s[80:81]
	v_mul_f32_e64 v32, v49, |v36|
	v_mul_f32_e32 v32, 0x3fb8aa3b, v32
	v_exp_f32_e32 v32, v32
	s_nop 0
	v_mul_f32_e32 v37, v32, v1
	v_and_b32_e32 v1, 0x7fffffff, v37
	v_lshlrev_b32_e64 v32, 1, v42
	v_cvt_pk_bf16_f32 v241, v37, s0
	ds_write_b16 v222, v241 offset:2
	v_mul_f32_e64 v33, v51, |v36|
	v_mul_f32_e32 v33, 0x3fb8aa3b, v33
	v_exp_f32_e32 v33, v33
	s_nop 0
	v_mul_f32_e64 v37, v33, v2
	v_and_b32_e32 v2, 0x7fffffff, v37
	v_cvt_pk_bf16_f32 v241, v37, s0
	ds_write_b16 v222, v241 offset:4
	v_mul_f32_e64 v33, v53, |v36|
	v_mul_f32_e32 v33, 0x3fb8aa3b, v33
	v_exp_f32_e32 v33, v33
	s_nop 0
	v_mul_f32_e64 v37, v33, v3
	v_and_b32_e32 v3, 0x7fffffff, v37
	v_cvt_pk_bf16_f32 v241, v37, s0
	ds_write_b16 v222, v241 offset:6
	v_mul_f32_e64 v33, v55, |v36|
	v_mul_f32_e32 v33, 0x3fb8aa3b, v33
	v_exp_f32_e32 v33, v33
	s_nop 0
	v_mul_f32_e64 v37, v33, v4
	v_and_b32_e32 v4, 0x7fffffff, v37
	v_cvt_pk_bf16_f32 v241, v37, s0
	ds_write_b16 v222, v241 offset:16
	v_mul_f32_e64 v33, v57, |v36|
	v_mul_f32_e32 v33, 0x3fb8aa3b, v33
	v_exp_f32_e32 v33, v33
	s_nop 0
	v_mul_f32_e64 v37, v33, v5
	v_and_b32_e32 v5, 0x7fffffff, v37
	v_cvt_pk_bf16_f32 v241, v37, s0
	ds_write_b16 v222, v241 offset:18
	v_mul_f32_e64 v33, v59, |v36|
	v_mul_f32_e32 v33, 0x3fb8aa3b, v33
	v_exp_f32_e32 v33, v33
	s_nop 0
	v_mul_f32_e64 v37, v33, v6
	v_and_b32_e32 v6, 0x7fffffff, v37
	v_cvt_pk_bf16_f32 v241, v37, s0
	ds_write_b16 v222, v241 offset:20
	v_mul_f32_e64 v33, v61, |v36|
	v_mul_f32_e32 v33, 0x3fb8aa3b, v33
	v_exp_f32_e32 v33, v33
	s_nop 0
	v_mul_f32_e64 v37, v33, v7
	v_and_b32_e32 v7, 0x7fffffff, v37
	v_cvt_pk_bf16_f32 v241, v37, s0
	ds_write_b16 v222, v241 offset:22
	v_mul_f32_e64 v33, v63, |v36|
	v_mul_f32_e32 v33, 0x3fb8aa3b, v33
	v_exp_f32_e32 v33, v33
	s_nop 0
	v_mul_f32_e64 v37, v33, v8
	v_and_b32_e32 v8, 0x7fffffff, v37
	v_cvt_pk_bf16_f32 v241, v37, s0
	ds_write_b16 v222, v241 offset:32
	v_mul_f32_e64 v33, v65, |v36|
	v_mul_f32_e32 v33, 0x3fb8aa3b, v33
	v_exp_f32_e32 v33, v33
	s_nop 0
	v_mul_f32_e64 v37, v33, v9
	v_and_b32_e32 v9, 0x7fffffff, v37
	v_cvt_pk_bf16_f32 v241, v37, s0
	ds_write_b16 v222, v241 offset:34
	v_mul_f32_e64 v33, v67, |v36|
	v_mul_f32_e32 v33, 0x3fb8aa3b, v33
	v_exp_f32_e32 v33, v33
	s_nop 0
	v_mul_f32_e64 v37, v33, v10
	v_and_b32_e32 v10, 0x7fffffff, v37
	v_cvt_pk_bf16_f32 v241, v37, s0
	ds_write_b16 v222, v241 offset:36
	v_mul_f32_e64 v33, v69, |v36|
	v_mul_f32_e32 v33, 0x3fb8aa3b, v33
	v_exp_f32_e32 v33, v33
	s_nop 0
	v_mul_f32_e64 v37, v33, v11
	v_and_b32_e32 v11, 0x7fffffff, v37
	v_cvt_pk_bf16_f32 v241, v37, s0
	ds_write_b16 v222, v241 offset:38
	v_mul_f32_e64 v33, v71, |v36|
	v_mul_f32_e32 v33, 0x3fb8aa3b, v33
	v_exp_f32_e32 v33, v33
	s_nop 0
	v_mul_f32_e64 v37, v33, v12
	v_and_b32_e32 v12, 0x7fffffff, v37
	v_cvt_pk_bf16_f32 v241, v37, s0
	ds_write_b16 v222, v241 offset:48
	v_mul_f32_e64 v33, v73, |v36|
	v_mul_f32_e32 v33, 0x3fb8aa3b, v33
	v_exp_f32_e32 v33, v33
	s_nop 0
	v_mul_f32_e64 v37, v33, v13
	v_and_b32_e32 v13, 0x7fffffff, v37
	v_cvt_pk_bf16_f32 v241, v37, s0
	ds_write_b16 v222, v241 offset:50
	v_mul_f32_e64 v33, v75, |v36|
	v_mul_f32_e32 v33, 0x3fb8aa3b, v33
	v_exp_f32_e32 v33, v33
	s_nop 0
	v_mul_f32_e64 v37, v33, v14
	v_and_b32_e32 v14, 0x7fffffff, v37
	v_cvt_pk_bf16_f32 v241, v37, s0
	ds_write_b16 v222, v241 offset:52
	v_mul_f32_e64 v33, v114, |v36|
	v_mul_f32_e32 v33, 0x3fb8aa3b, v33
	v_exp_f32_e32 v33, v33
	s_nop 0
	v_mul_f32_e64 v37, v33, v15
	v_and_b32_e32 v15, 0x7fffffff, v37
	v_cvt_pk_bf16_f32 v241, v37, s0
	ds_write_b16 v222, v241 offset:54
	s_and_saveexec_b64 s[78:79], s[74:75]
	s_cbranch_execz .LBB0_249

; DI u16 f2bf(float a) { return (u16)(pack2(a, 0.f) & 0xffffu); }
; DI int crow(int reg, int g) { return (reg & 3) + 8 * (reg >> 2) + 4 * g; }
; DI void filter_tile(const P& p, int l, int tile, char* smem) {
;     ...
; #pragma unroll
;       for (int reg = 0; reg < 16; ++reg) {
;         const int m = m0 + crow(reg, g);
;         const float t = (float)m / 8191.0f;
;         const float v = acc[reg] * __expf(-t * delta);
;         if (fwd) { tb[8192 - m] = f2bf(v); asum += fabsf(v); }
;         else if (m >= 1) { tb[8192 + m] = f2bf(v); asum += fabsf(v); }
;       }
;       if (fwd && tile == 0 && g == 0) tb[0] = 0;
;       asum += __shfl_xor(asum, 32);
;       if (g == 0) p.npart[(size_t)tile * 2048 + col] = asum;
.LBB0_249:
	s_or_b64 exec, exec, s[78:79]
	s_waitcnt lgkmcnt(0)
	ds_read_u16 v224, v223 offset:0
	ds_read_u16 v225, v223 offset:136
	ds_read_u16 v226, v223 offset:272
	ds_read_u16 v227, v223 offset:408
	ds_read_u16 v228, v223 offset:544
	ds_read_u16 v229, v223 offset:680
	ds_read_u16 v230, v223 offset:816
	ds_read_u16 v231, v223 offset:952
	ds_read_u16 v232, v223 offset:1088
	ds_read_u16 v233, v223 offset:1224
	ds_read_u16 v234, v223 offset:1360
	ds_read_u16 v235, v223 offset:1496
	ds_read_u16 v236, v223 offset:1632
	ds_read_u16 v237, v223 offset:1768
	ds_read_u16 v238, v223 offset:1904
	ds_read_u16 v239, v223 offset:2040
	v_readfirstlane_b32 s78, v34
	v_readfirstlane_b32 s79, v35
	v_mov_b32_e64 v246, v240
	v_and_b32_e32 v247, 0x7fff, v240
	v_cmp_eq_u32_e32 vcc, 0x4000, v247
	s_nop 1
	s_and_b64 s[80:81], vcc, s[6:7]
	s_andn2_b64 exec, exec, s[80:81]
	s_waitcnt lgkmcnt(0)
	global_store_short v246, v224, s[78:79]
	v_add_u32_e32 v246, 0x10000, v246
	global_store_short v246, v225, s[78:79]
	v_add_u32_e32 v246, 0x10000, v246
	global_store_short v246, v226, s[78:79]
	v_add_u32_e32 v246, 0x10000, v246
	global_store_short v246, v227, s[78:79]
	v_add_u32_e32 v246, 0x10000, v246
	global_store_short v246, v228, s[78:79]
	v_add_u32_e32 v246, 0x10000, v246
	global_store_short v246, v229, s[78:79]
	v_add_u32_e32 v246, 0x10000, v246
	global_store_short v246, v230, s[78:79]
	v_add_u32_e32 v246, 0x10000, v246
	global_store_short v246, v231, s[78:79]
	v_add_u32_e32 v246, 0x10000, v246
	global_store_short v246, v232, s[78:79]
	v_add_u32_e32 v246, 0x10000, v246
	global_store_short v246, v233, s[78:79]
	v_add_u32_e32 v246, 0x10000, v246
	global_store_short v246, v234, s[78:79]
	v_add_u32_e32 v246, 0x10000, v246
	global_store_short v246, v235, s[78:79]
	v_add_u32_e32 v246, 0x10000, v246
	global_store_short v246, v236, s[78:79]
	v_add_u32_e32 v246, 0x10000, v246
	global_store_short v246, v237, s[78:79]
	v_add_u32_e32 v246, 0x10000, v246
	global_store_short v246, v238, s[78:79]
	v_add_u32_e32 v246, 0x10000, v246
	global_store_short v246, v239, s[78:79]
	s_mov_b64 exec, -1
	v_add_f32_e32 v0, v0, v1
	v_add_f32_e32 v0, v0, v2
	v_add_f32_e32 v0, v0, v3
	v_add_f32_e32 v0, v0, v4
	v_add_f32_e32 v0, v0, v5
	v_add_f32_e32 v0, v0, v6
	v_add_f32_e32 v0, v0, v7
	v_add_f32_e32 v0, v0, v8
	v_add_f32_e32 v0, v0, v9
	v_add_f32_e32 v0, v0, v10
	v_add_f32_e32 v0, v0, v11
	v_add_f32_e32 v0, v0, v12
	v_add_f32_e32 v0, v0, v13
	v_add_f32_e32 v0, v0, v14
	v_add_f32_e32 v0, v0, v15
	ds_bpermute_b32 v1, v45, v0
	v_lshl_add_u64 v[34:35], v[76:77], 2, s[76:77]
	s_and_saveexec_b64 s[78:79], s[8:9]
	s_cbranch_execz .LBB0_251
	s_waitcnt lgkmcnt(0)
	v_add_f32_e32 v0, v0, v1
	global_store_dword v[34:35], v0, off
; #define MFMA(a, b, c) __builtin_amdgcn_mfma_f32_32x32x16_bf16((a), (b), (c), 0, 0, 0)
; DI u16 f2bf(float a) { return (u16)(pack2(a, 0.f) & 0xffffu); }
; DI int crow(int reg, int g) { return (reg & 3) + 8 * (reg >> 2) + 4 * g; }
; DI f32x16 zero16() { f32x16 z; for (int i = 0; i < 16; ++i) z[i] = 0.f; return z; }
; DI void filter_tile(const P& p, int l, int tile, char* smem) {
;     ...
; #pragma unroll
;     for (int u = 0; u < 2; ++u) {
;       const int col = wave * 256 + (nb + u) * 32 + li;
;       f32x16 acc = zero16();
; #pragma unroll
;       for (int ks = 0; ks < 4; ++ks) acc = MFMA(af[ks], __builtin_bit_cast(bf16x8, bw[u][ks]), acc);
;       const int j = col >> 9, c = col & 511;
;       const int order = j & 1;
;       const bool fwd = j < 2;
;       const float delta = fabsf(min_decay + (float)c * ((max_decay - min_decay) / 511.0f));
;       u16* tb = p.Tb + (size_t)(order * 512 + c) * 16384;
;       float asum = 0.f;
; #pragma unroll
;       for (int reg = 0; reg < 16; ++reg) {
;         const int m = m0 + crow(reg, g);
;         const float t = (float)m / 8191.0f;
;         const float v = acc[reg] * __expf(-t * delta);
;         if (fwd) { tb[8192 - m] = f2bf(v); asum += fabsf(v); }
;         else if (m >= 1) { tb[8192 + m] = f2bf(v); asum += fabsf(v); }
;       }
.LBB0_251:
	s_or_b64 exec, exec, s[78:79]
	s_waitcnt vmcnt(30)
	v_cvt_pk_bf16_f32 v0, v112, v113
	s_waitcnt vmcnt(28) lgkmcnt(0)
	v_cvt_pk_bf16_f32 v1, v115, v116
	s_waitcnt vmcnt(26)
	v_cvt_pk_bf16_f32 v2, v117, v118
	s_waitcnt vmcnt(24)
	v_cvt_pk_bf16_f32 v3, v119, v120
	s_waitcnt vmcnt(22)
	v_cvt_pk_bf16_f32 v116, v121, v122
	s_waitcnt vmcnt(19)
	v_cvt_pk_bf16_f32 v117, v123, v124
	v_mfma_f32_32x32x16_bf16 v[0:15], v[16:19], v[0:3], 0
	s_waitcnt vmcnt(17)
	v_cvt_pk_bf16_f32 v118, v125, v126
	s_waitcnt vmcnt(15)
	v_cvt_pk_bf16_f32 v119, v127, v128
	s_waitcnt vmcnt(13)
	v_cvt_pk_bf16_f32 v120, v129, v130
	s_waitcnt vmcnt(11)
	v_cvt_pk_bf16_f32 v121, v131, v132
	s_waitcnt vmcnt(9)
	v_cvt_pk_bf16_f32 v122, v133, v134
	s_waitcnt vmcnt(7)
	v_cvt_pk_bf16_f32 v123, v135, v136
	v_add_u32_e32 v33, 32, v76
	v_mfma_f32_32x32x16_bf16 v[0:15], v[20:23], v[116:119], v[0:15]
	v_and_b32_e32 v33, 0x1ff, v33
	v_cvt_f32_u32_e32 v37, v33
	s_waitcnt vmcnt(6)
	v_cvt_pk_bf16_f32 v116, v137, v138
	s_waitcnt vmcnt(4)
	v_cvt_pk_bf16_f32 v117, v139, v141
	s_waitcnt vmcnt(2)
	v_cvt_pk_bf16_f32 v118, v140, v142
	s_waitcnt vmcnt(0)
	v_cvt_pk_bf16_f32 v119, v143, v144
	v_fmamk_f32 v37, v37, 0xbcc4df2d, v201
	v_mfma_f32_32x32x16_bf16 v[0:15], v[24:27], v[120:123], v[0:15]
	v_mul_f32_e64 v39, v47, |v37|
	v_mul_f32_e32 v39, 0x3fb8aa3b, v39
	v_exp_f32_e32 v39, v39
	v_or_b32_e32 v33, v33, v43
	v_lshlrev_b32_e32 v188, 15, v33
	v_lshl_add_u64 v[112:113], s[44:45], 0, v[188:189]
	v_mfma_f32_32x32x16_bf16 v[0:15], v[28:31], v[116:119], v[0:15]
	s_nop 11
	v_mul_f32_e32 v39, v39, v0
	v_and_b32_e32 v0, 0x7fffffff, v39
	v_cvt_pk_bf16_f32 v241, v39, s0
	ds_write_b16 v222, v241 offset:0
	s_andn2_b64 s[80:81], s[6:7], s[10:11]
	v_cndmask_b32_e64 v0, v0, 0, s[80:81]
	v_mul_f32_e64 v33, v49, |v37|
	v_mul_f32_e32 v33, 0x3fb8aa3b, v33
	v_exp_f32_e32 v33, v33
	s_nop 0
	v_mul_f32_e32 v39, v33, v1
	v_and_b32_e32 v1, 0x7fffffff, v39
	v_cvt_pk_bf16_f32 v241, v39, s0
	ds_write_b16 v222, v241 offset:2
	v_mul_f32_e64 v33, v51, |v37|
	v_mul_f32_e32 v33, 0x3fb8aa3b, v33
	v_exp_f32_e32 v33, v33
	s_nop 0
	v_mul_f32_e64 v39, v33, v2
	v_and_b32_e32 v2, 0x7fffffff, v39
	v_cvt_pk_bf16_f32 v241, v39, s0
	ds_write_b16 v222, v241 offset:4
	v_mul_f32_e64 v33, v53, |v37|
	v_mul_f32_e32 v33, 0x3fb8aa3b, v33
	v_exp_f32_e32 v33, v33
	s_nop 0
	v_mul_f32_e64 v39, v33, v3
	v_and_b32_e32 v3, 0x7fffffff, v39
	v_cvt_pk_bf16_f32 v241, v39, s0
	ds_write_b16 v222, v241 offset:6
	v_mul_f32_e64 v33, v55, |v37|
	v_mul_f32_e32 v33, 0x3fb8aa3b, v33
	v_exp_f32_e32 v33, v33
	s_nop 0
	v_mul_f32_e64 v39, v33, v4
	v_and_b32_e32 v4, 0x7fffffff, v39
	v_cvt_pk_bf16_f32 v241, v39, s0
	ds_write_b16 v222, v241 offset:16
	v_mul_f32_e64 v33, v57, |v37|
	v_mul_f32_e32 v33, 0x3fb8aa3b, v33
	v_exp_f32_e32 v33, v33
	s_nop 0
	v_mul_f32_e64 v39, v33, v5
	v_and_b32_e32 v5, 0x7fffffff, v39
	v_cvt_pk_bf16_f32 v241, v39, s0
	ds_write_b16 v222, v241 offset:18
	v_mul_f32_e64 v33, v59, |v37|
	v_mul_f32_e32 v33, 0x3fb8aa3b, v33
	v_exp_f32_e32 v33, v33
	s_nop 0
	v_mul_f32_e64 v39, v33, v6
	v_and_b32_e32 v6, 0x7fffffff, v39
	v_cvt_pk_bf16_f32 v241, v39, s0
	ds_write_b16 v222, v241 offset:20
	v_mul_f32_e64 v33, v61, |v37|
	v_mul_f32_e32 v33, 0x3fb8aa3b, v33
	v_exp_f32_e32 v33, v33
	s_nop 0
	v_mul_f32_e64 v39, v33, v7
	v_and_b32_e32 v7, 0x7fffffff, v39
	v_cvt_pk_bf16_f32 v241, v39, s0
	ds_write_b16 v222, v241 offset:22
	v_mul_f32_e64 v33, v63, |v37|
	v_mul_f32_e32 v33, 0x3fb8aa3b, v33
	v_exp_f32_e32 v33, v33
	s_nop 0
	v_mul_f32_e64 v39, v33, v8
	v_and_b32_e32 v8, 0x7fffffff, v39
	v_cvt_pk_bf16_f32 v241, v39, s0
	ds_write_b16 v222, v241 offset:32
	v_mul_f32_e64 v33, v65, |v37|
	v_mul_f32_e32 v33, 0x3fb8aa3b, v33
	v_exp_f32_e32 v33, v33
	s_nop 0
	v_mul_f32_e64 v39, v33, v9
	v_and_b32_e32 v9, 0x7fffffff, v39
	v_cvt_pk_bf16_f32 v241, v39, s0
	ds_write_b16 v222, v241 offset:34
	v_mul_f32_e64 v33, v67, |v37|
	v_mul_f32_e32 v33, 0x3fb8aa3b, v33
	v_exp_f32_e32 v33, v33
	s_nop 0
	v_mul_f32_e64 v39, v33, v10
	v_and_b32_e32 v10, 0x7fffffff, v39
	v_cvt_pk_bf16_f32 v241, v39, s0
	ds_write_b16 v222, v241 offset:36
	v_mul_f32_e64 v33, v69, |v37|
	v_mul_f32_e32 v33, 0x3fb8aa3b, v33
	v_exp_f32_e32 v33, v33
	s_nop 0
	v_mul_f32_e64 v39, v33, v11
	v_and_b32_e32 v11, 0x7fffffff, v39
	v_cvt_pk_bf16_f32 v241, v39, s0
	ds_write_b16 v222, v241 offset:38
	v_mul_f32_e64 v33, v71, |v37|
	v_mul_f32_e32 v33, 0x3fb8aa3b, v33
	v_exp_f32_e32 v33, v33
	s_nop 0
	v_mul_f32_e64 v39, v33, v12
	v_and_b32_e32 v12, 0x7fffffff, v39
	v_cvt_pk_bf16_f32 v241, v39, s0
	ds_write_b16 v222, v241 offset:48
	v_mul_f32_e64 v33, v73, |v37|
	v_mul_f32_e32 v33, 0x3fb8aa3b, v33
	v_exp_f32_e32 v33, v33
	s_nop 0
	v_mul_f32_e64 v39, v33, v13
	v_and_b32_e32 v13, 0x7fffffff, v39
	v_cvt_pk_bf16_f32 v241, v39, s0
	ds_write_b16 v222, v241 offset:50
	v_mul_f32_e64 v33, v75, |v37|
	v_mul_f32_e32 v33, 0x3fb8aa3b, v33
	v_exp_f32_e32 v33, v33
	s_nop 0
	v_mul_f32_e64 v39, v33, v14
	v_and_b32_e32 v14, 0x7fffffff, v39
	v_cvt_pk_bf16_f32 v241, v39, s0
	ds_write_b16 v222, v241 offset:52
	v_mul_f32_e64 v33, v114, |v37|
	v_mul_f32_e32 v33, 0x3fb8aa3b, v33
	v_exp_f32_e32 v33, v33
	s_nop 0
	v_mul_f32_e64 v37, v33, v15
	v_and_b32_e32 v15, 0x7fffffff, v37
	v_cvt_pk_bf16_f32 v241, v37, s0
	ds_write_b16 v222, v241 offset:54
	s_and_saveexec_b64 s[78:79], s[74:75]
	s_cbranch_execz .LBB0_317

; DI u16 f2bf(float a) { return (u16)(pack2(a, 0.f) & 0xffffu); }
; DI int crow(int reg, int g) { return (reg & 3) + 8 * (reg >> 2) + 4 * g; }
; DI void filter_tile(const P& p, int l, int tile, char* smem) {
;     ...
; #pragma unroll
;       for (int reg = 0; reg < 16; ++reg) {
;         const int m = m0 + crow(reg, g);
;         const float t = (float)m / 8191.0f;
;         const float v = acc[reg] * __expf(-t * delta);
;         if (fwd) { tb[8192 - m] = f2bf(v); asum += fabsf(v); }
;         else if (m >= 1) { tb[8192 + m] = f2bf(v); asum += fabsf(v); }
;       }
;       if (fwd && tile == 0 && g == 0) tb[0] = 0;
;       asum += __shfl_xor(asum, 32);
;       if (g == 0) p.npart[(size_t)tile * 2048 + col] = asum;
;     }
;   }
.LBB0_317:
	s_or_b64 exec, exec, s[78:79]
	s_waitcnt lgkmcnt(0)
	ds_read_u16 v224, v223 offset:0
	ds_read_u16 v225, v223 offset:136
	ds_read_u16 v226, v223 offset:272
	ds_read_u16 v227, v223 offset:408
	ds_read_u16 v228, v223 offset:544
	ds_read_u16 v229, v223 offset:680
	ds_read_u16 v230, v223 offset:816
	ds_read_u16 v231, v223 offset:952
	ds_read_u16 v232, v223 offset:1088
	ds_read_u16 v233, v223 offset:1224
	ds_read_u16 v234, v223 offset:1360
	ds_read_u16 v235, v223 offset:1496
	ds_read_u16 v236, v223 offset:1632
	ds_read_u16 v237, v223 offset:1768
	ds_read_u16 v238, v223 offset:1904
	ds_read_u16 v239, v223 offset:2040
	v_readfirstlane_b32 s78, v112
	v_readfirstlane_b32 s79, v113
	v_mov_b32_e64 v246, v240
	v_and_b32_e32 v247, 0x7fff, v240
	v_cmp_eq_u32_e32 vcc, 0x4000, v247
	s_nop 1
	s_and_b64 s[80:81], vcc, s[6:7]
	s_andn2_b64 exec, exec, s[80:81]
	s_waitcnt lgkmcnt(0)
	global_store_short v246, v224, s[78:79]
	v_add_u32_e32 v246, 0x10000, v246
	global_store_short v246, v225, s[78:79]
	v_add_u32_e32 v246, 0x10000, v246
	global_store_short v246, v226, s[78:79]
	v_add_u32_e32 v246, 0x10000, v246
	global_store_short v246, v227, s[78:79]
	v_add_u32_e32 v246, 0x10000, v246
	global_store_short v246, v228, s[78:79]
	v_add_u32_e32 v246, 0x10000, v246
	global_store_short v246, v229, s[78:79]
	v_add_u32_e32 v246, 0x10000, v246
	global_store_short v246, v230, s[78:79]
	v_add_u32_e32 v246, 0x10000, v246
	global_store_short v246, v231, s[78:79]
	v_add_u32_e32 v246, 0x10000, v246
	global_store_short v246, v232, s[78:79]
	v_add_u32_e32 v246, 0x10000, v246
	global_store_short v246, v233, s[78:79]
	v_add_u32_e32 v246, 0x10000, v246
	global_store_short v246, v234, s[78:79]
	v_add_u32_e32 v246, 0x10000, v246
	global_store_short v246, v235, s[78:79]
	v_add_u32_e32 v246, 0x10000, v246
	global_store_short v246, v236, s[78:79]
	v_add_u32_e32 v246, 0x10000, v246
	global_store_short v246, v237, s[78:79]
	v_add_u32_e32 v246, 0x10000, v246
	global_store_short v246, v238, s[78:79]
	v_add_u32_e32 v246, 0x10000, v246
	global_store_short v246, v239, s[78:79]
	s_mov_b64 exec, -1
	v_add_f32_e32 v0, v0, v1
	v_add_f32_e32 v0, v0, v2
	v_add_f32_e32 v0, v0, v3
	v_add_f32_e32 v0, v0, v4
	v_add_f32_e32 v0, v0, v5
	v_add_f32_e32 v0, v0, v6
	v_add_f32_e32 v0, v0, v7
	v_add_f32_e32 v0, v0, v8
	v_add_f32_e32 v0, v0, v9
	v_add_f32_e32 v0, v0, v10
	v_add_f32_e32 v0, v0, v11
	v_add_f32_e32 v0, v0, v12
	v_add_f32_e32 v0, v0, v13
	v_add_f32_e32 v0, v0, v14
	v_add_f32_e32 v0, v0, v15
	ds_bpermute_b32 v1, v45, v0
	s_and_saveexec_b64 s[78:79], s[8:9]
	s_cbranch_execz .LBB0_182
	s_waitcnt lgkmcnt(0)
	v_add_f32_e32 v0, v0, v1
	global_store_dword v[34:35], v0, off offset:128
	s_branch .LBB0_182
	s_nop 0
